# attnA: the step's 4 LDS-DMA pieces issued one at a time in the VALU-only gaps of the second half of the step
# baseline (speedup 1.0000x reference)
; #define LAS __attribute__((address_space(3)))
; __device__ __forceinline__ float fexp2(float x) { return __builtin_amdgcn_exp2f(x); }
; #define MFMA32(a, b, c) __builtin_amdgcn_mfma_f32_32x32x16_bf16((a), (b), (c), 0, 0, 0)
; __device__ __forceinline__ bf16x8 v_build(const VRaw& r, int ks) { return (bf16x8){r.lo[ks][0], r.lo[ks][1], r.lo[ks][2], r.lo[ks][3], r.hv[ks][0], r.hv[ks][1], r.hv[ks][2], r.hv[ks][3]}; }
; #define A_MAX() \
;         float mx = fmaxf(s[0][0], s[1][0]); \
;         _Pragma("unroll") for (int r = 1; r < 16; ++r) mx = fmaxf(fmaxf(mx, s[0][r]), s[1][r]); \
;         mx = fmaxf(mx, __shfl_xor(mx, 32));
; __device__ __forceinline__ void attnA_unit(const P2Ctx& C, int b, int h, int qb) {
;     ...
;     for (int kt = 1; kt < NT; ++kt) {
;         if (kt + 2 < NT && !(pf & 16)) A_DMA(kt + 2);
;         if (kt < ntw) {
;             A_QK(kt)
;             if (!(pf & 4)) {
;             const LAS unsigned char* vimg = lds + ((kt - 1) & 3) * 32768 + 16384;
;             VRaw va;
;             v_issue<4>(vimg, 0, lane, va);
;             A_MAX()
;             float fres = 1.0f; bool resc = false;
;             if (__any(mx > ATHR)) {
;                 const float dl = fmaxf(mx, 0.f);
;                 mhat += dl;
;                 fres = fexp2(-dl); resc = true;
; #pragma unroll
;                 for (int kb2 = 0; kb2 < 2; ++kb2)
; #pragma unroll
;                     for (int r = 0; r < 16; ++r) s[kb2][r] -= dl;
;             }
;             float ps = 0.f;
;             v_wait(va);
;             __builtin_amdgcn_s_setprio(1);
; #pragma unroll
;             for (int ks = 0; ks < 4; ++ks) o[0] = MFMA32(v_build(va, ks), pf_[ks], o[0]);
.LaA_loop:
	s_cmp_lt_u32 s14, s13
	s_cbranch_scc0 .LaA_pvonly
	s_and_b32 s6, s14, 3
	s_lshl_b32 s6, s6, 15
	s_add_i32 s7, s14, -1
	s_and_b32 s7, s7, 3
	s_lshl_b32 s7, s7, 15
	v_add_u32_e32 v248, s6, v200
	v_add_u32_e32 v249, s6, v201
	v_add_u32_e32 v250, s6, v202
	v_add_u32_e32 v251, s6, v203
	v_add_u32_e32 v237, s7, v204
	ds_read_b128 v[100:103], v248
	ds_read_b128 v[104:107], v248 offset:4096
	ds_read_b128 v[108:111], v249
	ds_read_b128 v[112:115], v249 offset:4096
	ds_read_b128 v[116:119], v250
	ds_read_b128 v[120:123], v250 offset:4096
	ds_read_b128 v[124:127], v251
	ds_read_b128 v[128:131], v251 offset:4096
	s_waitcnt lgkmcnt(7)
	v_mfma_f32_32x32x16_bf16 v[68:83], v[100:103], v[164:167], v[220:235]
	ds_read_b64_tr_b16 v[132:133], v237 offset:0
	ds_read_b64_tr_b16 v[134:135], v237 offset:2048
	s_waitcnt lgkmcnt(8)
	v_mfma_f32_32x32x16_bf16 v[84:99], v[104:107], v[164:167], v[220:235]
	ds_read_b64_tr_b16 v[136:137], v237 offset:4096
	ds_read_b64_tr_b16 v[138:139], v237 offset:6144
	s_waitcnt lgkmcnt(9)
	v_mfma_f32_32x32x16_bf16 v[68:83], v[108:111], v[168:171], v[68:83]
	ds_read_b64_tr_b16 v[140:141], v237 offset:8192
	ds_read_b64_tr_b16 v[142:143], v237 offset:10240
	s_waitcnt lgkmcnt(10)
	v_mfma_f32_32x32x16_bf16 v[84:99], v[112:115], v[168:171], v[84:99]
	ds_read_b64_tr_b16 v[144:145], v237 offset:12288
	ds_read_b64_tr_b16 v[146:147], v237 offset:14336
	s_waitcnt lgkmcnt(11)
	v_mfma_f32_32x32x16_bf16 v[68:83], v[116:119], v[172:175], v[68:83]
	s_waitcnt lgkmcnt(10)
	v_mfma_f32_32x32x16_bf16 v[84:99], v[120:123], v[172:175], v[84:99]
	s_waitcnt lgkmcnt(9)
	v_mfma_f32_32x32x16_bf16 v[68:83], v[124:127], v[176:179], v[68:83]
	s_waitcnt lgkmcnt(8)
	v_mfma_f32_32x32x16_bf16 v[84:99], v[128:131], v[176:179], v[84:99]
	s_waitcnt lgkmcnt(0)
	ds_read_b64_tr_b16 v[148:149], v237 offset:512
	ds_read_b64_tr_b16 v[150:151], v237 offset:2560
	v_mfma_f32_32x32x16_bf16 v[4:19], v[132:135], v[180:183], v[4:19]
	ds_read_b64_tr_b16 v[152:153], v237 offset:4608
	ds_read_b64_tr_b16 v[154:155], v237 offset:6656
	ds_read_b64_tr_b16 v[156:157], v237 offset:8704
	v_mfma_f32_32x32x16_bf16 v[4:19], v[136:139], v[184:187], v[4:19]
	ds_read_b64_tr_b16 v[158:159], v237 offset:10752
	ds_read_b64_tr_b16 v[160:161], v237 offset:12800
	ds_read_b64_tr_b16 v[162:163], v237 offset:14848
	v_mfma_f32_32x32x16_bf16 v[4:19], v[140:143], v[188:191], v[4:19]
	v_mfma_f32_32x32x16_bf16 v[4:19], v[144:147], v[192:195], v[4:19]
	s_lshl_b32 s6, s14, 6
	s_cmp_gt_i32 s6, s26
	s_cbranch_scc1 .LaA_near_7

; #define MFMA32(a, b, c) __builtin_amdgcn_mfma_f32_32x32x16_bf16((a), (b), (c), 0, 0, 0)
; __device__ __forceinline__ bf16x8 v_build(const VRaw& r, int ks) { return (bf16x8){r.lo[ks][0], r.lo[ks][1], r.lo[ks][2], r.lo[ks][3], r.hv[ks][0], r.hv[ks][1], r.hv[ks][2], r.hv[ks][3]}; }
; #define SB_ __builtin_amdgcn_sched_barrier(0)
; #define EX4_(S, B) do { S[B] = fexp2(S[B]); S[B + 1] = fexp2(S[B + 1]); S[B + 2] = fexp2(S[B + 2]); S[B + 3] = fexp2(S[B + 3]); } while (0)
; #define SUM8_(S, B) do { ps += ((S[B] + S[B + 1]) + (S[B + 2] + S[B + 3])) + ((S[B + 4] + S[B + 5]) + (S[B + 6] + S[B + 7])); } while (0)
; __device__ __forceinline__ void attnA_unit(const P2Ctx& C, int b, int h, int qb) {
;     ...
;             EX4_(s[0], 0); EX4_(s[0], 4); EX4_(s[0], 8); EX4_(s[0], 12);
;             SB_; v_issue<4>(vimg, 1, lane, va); v_wait(va);
; #pragma unroll
;             for (int ks = 0; ks < 4; ++ks) o[1] = MFMA32(v_build(va, ks), pf_[ks], o[1]);
;             EX4_(s[1], 0); EX4_(s[1], 4); EX4_(s[1], 8); EX4_(s[1], 12);
;             SB_; v_issue<4>(vimg, 2, lane, va); v_wait(va);
; #pragma unroll
;             for (int ks = 0; ks < 4; ++ks) o[2] = MFMA32(v_build(va, ks), pf_[ks], o[2]);
;             SUM8_(s[0], 0); SUM8_(s[0], 8); SUM8_(s[1], 0); SUM8_(s[1], 8);
;             SB_; v_issue<4>(vimg, 3, lane, va); v_wait(va);
;             o[3] = MFMA32(v_build(va, 0), pf_[0], o[3]); pf_[0] = pack_p(s[0], 0);
;             o[3] = MFMA32(v_build(va, 1), pf_[1], o[3]); pf_[1] = pack_p(s[0], 1);
;             o[3] = MFMA32(v_build(va, 2), pf_[2], o[3]); pf_[2] = pack_p(s[1], 0);
;             o[3] = MFMA32(v_build(va, 3), pf_[3], o[3]); pf_[3] = pack_p(s[1], 1);
.LaA_resc_back:
	s_waitcnt lgkmcnt(0)
	s_cmp_lt_u32 s24, s12
	s_cselect_b32 s90, 1, 0
	s_and_b32 s6, s24, 3
	s_lshl_b32 s6, s6, 15
	s_add_i32 s7, s6, s22
	s_add_i32 s29, s6, s23
	s_add_u32 s20, s16, 0x80
	s_addc_u32 s21, s17, 0
	ds_read_b64_tr_b16 v[148:149], v237 offset:1536
	ds_read_b64_tr_b16 v[150:151], v237 offset:3584
	v_mfma_f32_32x32x16_bf16 v[36:51], v[132:135], v[180:183], v[36:51]
	ds_read_b64_tr_b16 v[152:153], v237 offset:5632
	ds_read_b64_tr_b16 v[154:155], v237 offset:7680
	ds_read_b64_tr_b16 v[156:157], v237 offset:9728
	v_exp_f32_e32 v68, v68
	v_exp_f32_e32 v69, v69
	v_exp_f32_e32 v70, v70
	v_exp_f32_e32 v71, v71
	v_mfma_f32_32x32x16_bf16 v[36:51], v[136:139], v[184:187], v[36:51]
	ds_read_b64_tr_b16 v[158:159], v237 offset:11776
	ds_read_b64_tr_b16 v[160:161], v237 offset:13824
	ds_read_b64_tr_b16 v[162:163], v237 offset:15872
	v_exp_f32_e32 v72, v72
	v_exp_f32_e32 v73, v73
	v_exp_f32_e32 v74, v74
	v_exp_f32_e32 v75, v75
	v_mfma_f32_32x32x16_bf16 v[36:51], v[140:143], v[188:191], v[36:51]
	s_mov_b32 m0, s7
	v_exp_f32_e32 v76, v76
	v_exp_f32_e32 v77, v77
	v_exp_f32_e32 v78, v78
	v_exp_f32_e32 v79, v79
	s_cmp_lg_u32 s90, 0
	s_cbranch_scc0 .LaA_lp_9
	global_load_lds_dwordx4 v197, s[16:17]
.LaA_lp_9:
	s_add_i32 m0, s7, 0x2000
	v_mfma_f32_32x32x16_bf16 v[36:51], v[144:147], v[192:195], v[36:51]
	v_exp_f32_e32 v80, v80
	v_exp_f32_e32 v81, v81
	v_exp_f32_e32 v82, v82
	v_exp_f32_e32 v83, v83
	s_cmp_lg_u32 s90, 0
	s_cbranch_scc0 .LaA_lp_10
	global_load_lds_dwordx4 v197, s[20:21]
.LaA_lp_10:
	s_mov_b32 m0, s29
	s_add_u32 s20, s18, 0x80
	s_addc_u32 s21, s19, 0
	s_waitcnt lgkmcnt(0)
	v_mfma_f32_32x32x16_bf16 v[52:67], v[148:151], v[180:183], v[52:67]
	v_exp_f32_e32 v84, v84
	v_exp_f32_e32 v85, v85
	v_exp_f32_e32 v86, v86
	v_exp_f32_e32 v87, v87
	v_exp_f32_e32 v88, v88
	v_exp_f32_e32 v89, v89
	v_exp_f32_e32 v90, v90
	v_exp_f32_e32 v91, v91
	s_cmp_lg_u32 s90, 0
	s_cbranch_scc0 .LaA_lp_11
	global_load_lds_dwordx4 v198, s[18:19]
.LaA_lp_11:
	s_add_i32 m0, s29, 0x400
	v_cvt_pk_bf16_f32 v180, v68, v69
	v_cvt_pk_bf16_f32 v181, v70, v71
	v_cvt_pk_bf16_f32 v182, v72, v73
	v_cvt_pk_bf16_f32 v183, v74, v75
	v_mfma_f32_32x32x16_bf16 v[52:67], v[152:155], v[184:187], v[52:67]
	v_exp_f32_e32 v92, v92
	v_exp_f32_e32 v93, v93
	v_exp_f32_e32 v94, v94
	v_exp_f32_e32 v95, v95
	v_exp_f32_e32 v96, v96
	v_exp_f32_e32 v97, v97
	v_exp_f32_e32 v98, v98
	v_exp_f32_e32 v99, v99
	s_cmp_lg_u32 s90, 0
	s_cbranch_scc0 .LaA_lp_12
	global_load_lds_dwordx4 v198, s[20:21]
.LaA_lp_12:
	s_cmp_lg_u32 s90, 0
	s_cbranch_scc0 .LaA_la_13
	s_add_u32 s16, s16, 0x20000
	s_addc_u32 s17, s17, 0
	s_add_u32 s18, s18, 0x20000
	s_addc_u32 s19, s19, 0
	s_add_i32 s24, s24, 1
.LaA_la_13:
	v_cvt_pk_bf16_f32 v184, v76, v77
	v_cvt_pk_bf16_f32 v185, v78, v79
	v_cvt_pk_bf16_f32 v186, v80, v81
	v_cvt_pk_bf16_f32 v187, v82, v83
	v_mfma_f32_32x32x16_bf16 v[52:67], v[156:159], v[188:191], v[52:67]
	v_add_f32_e32 v245, v68, v69
	v_add_f32_e32 v243, v70, v71
	v_add_f32_e32 v245, v245, v243
	v_add_f32_e32 v243, v72, v73
	v_add_f32_e32 v242, v74, v75
	v_add_f32_e32 v243, v243, v242
	v_add_f32_e32 v245, v245, v243
	v_add_f32_e32 v246, v76, v77
	v_add_f32_e32 v243, v78, v79
	v_add_f32_e32 v246, v246, v243
	v_add_f32_e32 v243, v80, v81
	v_add_f32_e32 v242, v82, v83
	v_add_f32_e32 v243, v243, v242
	v_add_f32_e32 v246, v246, v243
	v_add_f32_e32 v245, v245, v246
	v_cvt_pk_bf16_f32 v188, v84, v85
	v_cvt_pk_bf16_f32 v189, v86, v87
	v_cvt_pk_bf16_f32 v190, v88, v89
	v_cvt_pk_bf16_f32 v191, v90, v91
	v_mfma_f32_32x32x16_bf16 v[52:67], v[160:163], v[192:195], v[52:67]
	v_add_f32_e32 v246, v84, v85
	v_add_f32_e32 v243, v86, v87
	v_add_f32_e32 v246, v246, v243
	v_add_f32_e32 v243, v88, v89
	v_add_f32_e32 v242, v90, v91
	v_add_f32_e32 v243, v243, v242
	v_add_f32_e32 v246, v246, v243
	v_add_f32_e32 v245, v245, v246
	v_add_f32_e32 v246, v92, v93
	v_add_f32_e32 v243, v94, v95
	v_add_f32_e32 v246, v246, v243
	v_add_f32_e32 v243, v96, v97
	v_add_f32_e32 v242, v98, v99
	v_add_f32_e32 v243, v243, v242
	v_add_f32_e32 v246, v246, v243
	v_add_f32_e32 v245, v245, v246
	v_cvt_pk_bf16_f32 v192, v92, v93
	v_cvt_pk_bf16_f32 v193, v94, v95
	v_cvt_pk_bf16_f32 v194, v96, v97
	v_cvt_pk_bf16_f32 v195, v98, v99
	s_cmp_lg_u32 s25, 0
	s_cbranch_scc1 .LaA_resc_post

; __device__ __forceinline__ void attnA_unit(const P2Ctx& C, int b, int h, int qb) {
;     ...
;             if (resc) {
;                 l *= fres;
; #pragma unroll
;                 for (int cb = 0; cb < 4; ++cb)
; #pragma unroll
;                     for (int r = 0; r < 16; ++r) o[cb][r] *= fres;
;             }
;             l += ps;
;             }
;         } else if (kt - 1 < ntw && !(pf & 2)) { A_PV(kt - 1); }
.LaA_resc_post:
	s_nop 7
	s_nop 3
	v_mul_f32_e32 v4, v244, v4
	v_mul_f32_e32 v5, v244, v5
	v_mul_f32_e32 v6, v244, v6
	v_mul_f32_e32 v7, v244, v7
	v_mul_f32_e32 v8, v244, v8
	v_mul_f32_e32 v9, v244, v9
	v_mul_f32_e32 v10, v244, v10
	v_mul_f32_e32 v11, v244, v11
	v_mul_f32_e32 v12, v244, v12
	v_mul_f32_e32 v13, v244, v13
	v_mul_f32_e32 v14, v244, v14
	v_mul_f32_e32 v15, v244, v15
	v_mul_f32_e32 v16, v244, v16
	v_mul_f32_e32 v17, v244, v17
	v_mul_f32_e32 v18, v244, v18
	v_mul_f32_e32 v19, v244, v19
	v_mul_f32_e32 v20, v244, v20
	v_mul_f32_e32 v21, v244, v21
	v_mul_f32_e32 v22, v244, v22
	v_mul_f32_e32 v23, v244, v23
	v_mul_f32_e32 v24, v244, v24
	v_mul_f32_e32 v25, v244, v25
	v_mul_f32_e32 v26, v244, v26
	v_mul_f32_e32 v27, v244, v27
	v_mul_f32_e32 v28, v244, v28
	v_mul_f32_e32 v29, v244, v29
	v_mul_f32_e32 v30, v244, v30
	v_mul_f32_e32 v31, v244, v31
	v_mul_f32_e32 v32, v244, v32
	v_mul_f32_e32 v33, v244, v33
	v_mul_f32_e32 v34, v244, v34
	v_mul_f32_e32 v35, v244, v35
	v_mul_f32_e32 v36, v244, v36
	v_mul_f32_e32 v37, v244, v37
	v_mul_f32_e32 v38, v244, v38
	v_mul_f32_e32 v39, v244, v39
	v_mul_f32_e32 v40, v244, v40
	v_mul_f32_e32 v41, v244, v41
	v_mul_f32_e32 v42, v244, v42
	v_mul_f32_e32 v43, v244, v43
	v_mul_f32_e32 v44, v244, v44
	v_mul_f32_e32 v45, v244, v45
	v_mul_f32_e32 v46, v244, v46
	v_mul_f32_e32 v47, v244, v47
	v_mul_f32_e32 v48, v244, v48
	v_mul_f32_e32 v49, v244, v49
	v_mul_f32_e32 v50, v244, v50
	v_mul_f32_e32 v51, v244, v51
	v_mul_f32_e32 v52, v244, v52
	v_mul_f32_e32 v53, v244, v53
	v_mul_f32_e32 v54, v244, v54
	v_mul_f32_e32 v55, v244, v55
	v_mul_f32_e32 v56, v244, v56
	v_mul_f32_e32 v57, v244, v57
	v_mul_f32_e32 v58, v244, v58
	v_mul_f32_e32 v59, v244, v59
	v_mul_f32_e32 v60, v244, v60
	v_mul_f32_e32 v61, v244, v61
	v_mul_f32_e32 v62, v244, v62
	v_mul_f32_e32 v63, v244, v63
	v_mul_f32_e32 v64, v244, v64
	v_mul_f32_e32 v65, v244, v65
	v_mul_f32_e32 v66, v244, v66
	v_mul_f32_e32 v67, v244, v67
	v_mul_f32_e32 v241, v244, v241
	s_mov_b32 s25, 0
	s_branch .LaA_resc_done
.LaA_pvonly:
	s_cmp_eq_u32 s14, s13
	s_cbranch_scc0 .LaA_pvskip_16
	s_add_i32 s7, s14, -1
	s_and_b32 s7, s7, 3
	s_lshl_b32 s7, s7, 15
	v_add_u32_e32 v237, s7, v204
	ds_read_b64_tr_b16 v[132:133], v237 offset:0
	ds_read_b64_tr_b16 v[134:135], v237 offset:2048
	ds_read_b64_tr_b16 v[136:137], v237 offset:4096
	ds_read_b64_tr_b16 v[138:139], v237 offset:6144
	ds_read_b64_tr_b16 v[140:141], v237 offset:8192
	ds_read_b64_tr_b16 v[142:143], v237 offset:10240
	ds_read_b64_tr_b16 v[144:145], v237 offset:12288
	ds_read_b64_tr_b16 v[146:147], v237 offset:14336
	s_waitcnt lgkmcnt(0)
	ds_read_b64_tr_b16 v[148:149], v237 offset:512
	ds_read_b64_tr_b16 v[150:151], v237 offset:2560
	v_mfma_f32_32x32x16_bf16 v[4:19], v[132:135], v[180:183], v[4:19]
	ds_read_b64_tr_b16 v[152:153], v237 offset:4608
	ds_read_b64_tr_b16 v[154:155], v237 offset:6656
	ds_read_b64_tr_b16 v[156:157], v237 offset:8704
	v_mfma_f32_32x32x16_bf16 v[4:19], v[136:139], v[184:187], v[4:19]
	ds_read_b64_tr_b16 v[158:159], v237 offset:10752
	ds_read_b64_tr_b16 v[160:161], v237 offset:12800
	ds_read_b64_tr_b16 v[162:163], v237 offset:14848
	v_mfma_f32_32x32x16_bf16 v[4:19], v[140:143], v[188:191], v[4:19]
	v_mfma_f32_32x32x16_bf16 v[4:19], v[144:147], v[192:195], v[4:19]
	s_waitcnt lgkmcnt(0)
	ds_read_b64_tr_b16 v[132:133], v237 offset:1024
	ds_read_b64_tr_b16 v[134:135], v237 offset:3072
	v_mfma_f32_32x32x16_bf16 v[20:35], v[148:151], v[180:183], v[20:35]
	ds_read_b64_tr_b16 v[136:137], v237 offset:5120
	ds_read_b64_tr_b16 v[138:139], v237 offset:7168
	ds_read_b64_tr_b16 v[140:141], v237 offset:9216
	v_mfma_f32_32x32x16_bf16 v[20:35], v[152:155], v[184:187], v[20:35]
	ds_read_b64_tr_b16 v[142:143], v237 offset:11264
	ds_read_b64_tr_b16 v[144:145], v237 offset:13312
	ds_read_b64_tr_b16 v[146:147], v237 offset:15360
	v_mfma_f32_32x32x16_bf16 v[20:35], v[156:159], v[188:191], v[20:35]
	v_mfma_f32_32x32x16_bf16 v[20:35], v[160:163], v[192:195], v[20:35]
	s_waitcnt lgkmcnt(0)
	ds_read_b64_tr_b16 v[148:149], v237 offset:1536
	ds_read_b64_tr_b16 v[150:151], v237 offset:3584
	v_mfma_f32_32x32x16_bf16 v[36:51], v[132:135], v[180:183], v[36:51]
	ds_read_b64_tr_b16 v[152:153], v237 offset:5632
	ds_read_b64_tr_b16 v[154:155], v237 offset:7680
	ds_read_b64_tr_b16 v[156:157], v237 offset:9728
	v_mfma_f32_32x32x16_bf16 v[36:51], v[136:139], v[184:187], v[36:51]
	ds_read_b64_tr_b16 v[158:159], v237 offset:11776
	ds_read_b64_tr_b16 v[160:161], v237 offset:13824
	ds_read_b64_tr_b16 v[162:163], v237 offset:15872
	v_mfma_f32_32x32x16_bf16 v[36:51], v[140:143], v[188:191], v[36:51]
	v_mfma_f32_32x32x16_bf16 v[36:51], v[144:147], v[192:195], v[36:51]
	s_waitcnt lgkmcnt(0)
	v_mfma_f32_32x32x16_bf16 v[52:67], v[148:151], v[180:183], v[52:67]
	v_mfma_f32_32x32x16_bf16 v[52:67], v[152:155], v[184:187], v[52:67]
	v_mfma_f32_32x32x16_bf16 v[52:67], v[156:159], v[188:191], v[52:67]
	v_mfma_f32_32x32x16_bf16 v[52:67], v[160:163], v[192:195], v[52:67]

; #define LAS __attribute__((address_space(3)))
; __device__ __forceinline__ void attnA_unit(const P2Ctx& C, int b, int h, int qb) {
;     ...
;     if (NT - 1 < ntw && !(pf & 2)) A_PV(NT - 1);
;     __syncthreads();
;     ...
;     l += __shfl_xor(l, 32);
;     const float inv = 1.0f / l;
;     LAS float* X2 = (LAS float*)(lds + 65536);
;     if (comp == 1) {
; #pragma unroll
;         for (int cb = 0; cb < 4; ++cb)
; #pragma unroll
;             for (int r = 0; r < 16; ++r) X2[((qs * 4 + cb) * 16 + r) * 64 + lane] = o[cb][r] * inv;
;     }
.LaA_nofinalpv_17:
	s_waitcnt lgkmcnt(0)
	s_barrier
	v_mov_b32_e32 v243, v241
	s_nop 1
	v_permlane32_swap_b32 v243, v241
	v_add_f32_e32 v241, v243, v241
	v_rcp_f32_e32 v241, v241
	s_lshl_b32 s6, s9, 14
	s_add_i32 s6, s6, 0x10000
	v_lshlrev_b32_e32 v2, 2, v219
	v_add_u32_e32 v2, s6, v2
	s_cmp_eq_u32 s8, 0
	s_cbranch_scc1 .LaA_comp0_18
	s_nop 7
	s_nop 3
	v_mul_f32_e32 v68, v4, v241
	ds_write_b32 v2, v68 offset:0
	v_mul_f32_e32 v69, v5, v241
	ds_write_b32 v2, v69 offset:256
	v_mul_f32_e32 v68, v6, v241
	ds_write_b32 v2, v68 offset:512
	v_mul_f32_e32 v69, v7, v241
	ds_write_b32 v2, v69 offset:768
	v_mul_f32_e32 v68, v8, v241
	ds_write_b32 v2, v68 offset:1024
	v_mul_f32_e32 v69, v9, v241
	ds_write_b32 v2, v69 offset:1280
	v_mul_f32_e32 v68, v10, v241
	ds_write_b32 v2, v68 offset:1536
	v_mul_f32_e32 v69, v11, v241
	ds_write_b32 v2, v69 offset:1792
	v_mul_f32_e32 v68, v12, v241
	ds_write_b32 v2, v68 offset:2048
	v_mul_f32_e32 v69, v13, v241
	ds_write_b32 v2, v69 offset:2304
	v_mul_f32_e32 v68, v14, v241
	ds_write_b32 v2, v68 offset:2560
	v_mul_f32_e32 v69, v15, v241
	ds_write_b32 v2, v69 offset:2816
	v_mul_f32_e32 v68, v16, v241
	ds_write_b32 v2, v68 offset:3072
	v_mul_f32_e32 v69, v17, v241
	ds_write_b32 v2, v69 offset:3328
	v_mul_f32_e32 v68, v18, v241
	ds_write_b32 v2, v68 offset:3584
	v_mul_f32_e32 v69, v19, v241
	ds_write_b32 v2, v69 offset:3840
	v_mul_f32_e32 v68, v20, v241
	ds_write_b32 v2, v68 offset:4096
	v_mul_f32_e32 v69, v21, v241
	ds_write_b32 v2, v69 offset:4352
	v_mul_f32_e32 v68, v22, v241
	ds_write_b32 v2, v68 offset:4608
	v_mul_f32_e32 v69, v23, v241
	ds_write_b32 v2, v69 offset:4864
	v_mul_f32_e32 v68, v24, v241
	ds_write_b32 v2, v68 offset:5120
	v_mul_f32_e32 v69, v25, v241
	ds_write_b32 v2, v69 offset:5376
	v_mul_f32_e32 v68, v26, v241
	ds_write_b32 v2, v68 offset:5632
	v_mul_f32_e32 v69, v27, v241
	ds_write_b32 v2, v69 offset:5888
	v_mul_f32_e32 v68, v28, v241
	ds_write_b32 v2, v68 offset:6144
	v_mul_f32_e32 v69, v29, v241
	ds_write_b32 v2, v69 offset:6400
	v_mul_f32_e32 v68, v30, v241
	ds_write_b32 v2, v68 offset:6656
	v_mul_f32_e32 v69, v31, v241
	ds_write_b32 v2, v69 offset:6912
	v_mul_f32_e32 v68, v32, v241
	ds_write_b32 v2, v68 offset:7168
	v_mul_f32_e32 v69, v33, v241
	ds_write_b32 v2, v69 offset:7424
	v_mul_f32_e32 v68, v34, v241
	ds_write_b32 v2, v68 offset:7680
	v_mul_f32_e32 v69, v35, v241
	ds_write_b32 v2, v69 offset:7936
	v_mul_f32_e32 v68, v36, v241
	ds_write_b32 v2, v68 offset:8192
	v_mul_f32_e32 v69, v37, v241
	ds_write_b32 v2, v69 offset:8448
	v_mul_f32_e32 v68, v38, v241
	ds_write_b32 v2, v68 offset:8704
	v_mul_f32_e32 v69, v39, v241
	ds_write_b32 v2, v69 offset:8960
	v_mul_f32_e32 v68, v40, v241
	ds_write_b32 v2, v68 offset:9216
	v_mul_f32_e32 v69, v41, v241
	ds_write_b32 v2, v69 offset:9472
	v_mul_f32_e32 v68, v42, v241
	ds_write_b32 v2, v68 offset:9728
	v_mul_f32_e32 v69, v43, v241
	ds_write_b32 v2, v69 offset:9984
	v_mul_f32_e32 v68, v44, v241
	ds_write_b32 v2, v68 offset:10240
	v_mul_f32_e32 v69, v45, v241
	ds_write_b32 v2, v69 offset:10496
	v_mul_f32_e32 v68, v46, v241
	ds_write_b32 v2, v68 offset:10752
	v_mul_f32_e32 v69, v47, v241
	ds_write_b32 v2, v69 offset:11008
	v_mul_f32_e32 v68, v48, v241
	ds_write_b32 v2, v68 offset:11264
	v_mul_f32_e32 v69, v49, v241
	ds_write_b32 v2, v69 offset:11520
	v_mul_f32_e32 v68, v50, v241
	ds_write_b32 v2, v68 offset:11776
	v_mul_f32_e32 v69, v51, v241
	ds_write_b32 v2, v69 offset:12032
	v_mul_f32_e32 v68, v52, v241
	ds_write_b32 v2, v68 offset:12288
	v_mul_f32_e32 v69, v53, v241
	ds_write_b32 v2, v69 offset:12544
	v_mul_f32_e32 v68, v54, v241
	ds_write_b32 v2, v68 offset:12800
	v_mul_f32_e32 v69, v55, v241
	ds_write_b32 v2, v69 offset:13056
	v_mul_f32_e32 v68, v56, v241
	ds_write_b32 v2, v68 offset:13312
	v_mul_f32_e32 v69, v57, v241
	ds_write_b32 v2, v69 offset:13568
	v_mul_f32_e32 v68, v58, v241
	ds_write_b32 v2, v68 offset:13824
	v_mul_f32_e32 v69, v59, v241
	ds_write_b32 v2, v69 offset:14080
	v_mul_f32_e32 v68, v60, v241
	ds_write_b32 v2, v68 offset:14336
	v_mul_f32_e32 v69, v61, v241
	ds_write_b32 v2, v69 offset:14592
	v_mul_f32_e32 v68, v62, v241
	ds_write_b32 v2, v68 offset:14848
	v_mul_f32_e32 v69, v63, v241
	ds_write_b32 v2, v69 offset:15104
	v_mul_f32_e32 v68, v64, v241
	ds_write_b32 v2, v68 offset:15360
	v_mul_f32_e32 v69, v65, v241
	ds_write_b32 v2, v69 offset:15616
	v_mul_f32_e32 v68, v66, v241
	ds_write_b32 v2, v68 offset:15872
	v_mul_f32_e32 v69, v67, v241
	ds_write_b32 v2, v69 offset:16128
	s_waitcnt lgkmcnt(0)
	s_barrier
	s_branch .LaA_epiend_19
; __device__ __forceinline__ void attnA_unit(const P2Ctx& C, int b, int h, int qb) {
;     ...
;     if (comp == 1) {
; #pragma unroll
;         for (int cb = 0; cb < 4; ++cb)
; #pragma unroll
;             for (int r = 0; r < 16; ++r) X2[((qs * 4 + cb) * 16 + r) * 64 + lane] = o[cb][r] * inv;
;     }
;     __syncthreads();
;     if (comp == 0) {
	s_nop 0
	s_nop 0
	s_nop 0
	s_nop 0
	s_nop 0
	s_nop 0
	s_nop 0
	s_nop 0
	s_nop 0
	s_nop 0
	s_nop 0
	s_nop 0
	s_nop 0
	s_nop 0
	s_nop 0
	s_nop 0
	s_nop 0
	s_nop 0
	s_nop 0
	s_nop 0
	s_nop 0
	s_nop 0
	s_nop 0
	s_nop 0
	s_nop 0
	s_nop 0
	s_nop 0
	s_nop 0
	s_nop 0
	s_nop 0
	s_nop 0
	s_nop 0
	s_nop 0
	s_nop 0
	s_nop 0
	s_nop 0
	s_nop 0
	s_nop 0
	s_nop 0
	s_nop 0
	s_nop 0
	s_nop 0
	s_nop 0
	s_nop 0
	s_nop 0
	s_nop 0
	s_nop 0
	s_nop 0
	s_nop 0
	s_nop 0
	s_nop 0
	s_nop 0
	s_nop 0
	s_nop 0
	s_nop 0
	s_nop 0
	s_nop 0
	s_nop 0
	s_nop 0
	s_nop 0
	s_nop 0
	s_nop 0
	s_nop 0
	s_nop 0
	s_nop 0
	s_nop 0
	s_nop 0
	s_nop 0
	s_nop 0
	s_nop 0
	s_nop 0
	s_nop 0
	s_nop 0
	s_nop 0
	s_nop 0
	s_nop 0
	s_nop 0
	s_nop 0
	s_nop 0
	s_nop 0
	s_nop 0
	s_nop 0
	s_nop 0
	s_nop 0
	s_nop 0
	s_nop 0
	s_nop 0
	s_nop 0
	s_nop 0
	s_nop 0
	s_nop 0
	s_nop 0
	s_nop 0
	s_nop 0
	s_nop 0
	s_nop 0
	s_nop 0
	s_nop 0
	s_nop 0
	s_nop 0
	s_nop 0
	s_nop 0
	s_nop 0
	s_nop 0
	s_nop 0
	s_nop 0
	s_nop 0
	s_nop 0
	s_nop 0
	s_nop 0
	s_nop 0
	s_nop 0
	s_nop 0
	s_nop 0
	s_nop 0
	s_nop 0
	s_nop 0
	s_nop 0
	s_nop 0
	s_nop 0
	s_nop 0
	s_nop 0
	s_nop 0
	s_nop 0
	s_nop 0
	s_nop 0
	s_nop 0
	s_nop 0
	s_nop 0
	s_nop 0
	s_nop 0
	s_nop 0
	s_nop 0
	s_nop 0
	s_nop 0
	s_nop 0
	s_nop 0
	s_nop 0
	s_nop 0
	s_nop 0
	s_nop 0
	s_nop 0
	s_nop 0
	s_nop 0
	s_nop 0
	s_nop 0
	s_nop 0
	s_nop 0
	s_nop 0
	s_nop 0
	s_nop 0
	s_nop 0
	s_nop 0
	s_nop 0
	s_nop 0
	s_nop 0
	s_nop 0
	s_nop 0
	s_nop 0
	s_nop 0
	s_nop 0
	s_nop 0
	s_nop 0
	s_nop 0
	s_nop 0
	s_nop 0
	s_nop 0
	s_nop 0
	s_nop 0
	s_nop 0
	s_nop 0
	s_nop 0
	s_nop 0
	s_nop 0
	s_nop 0
	s_nop 0
	s_nop 0
	s_nop 0
	s_nop 0
	s_nop 0
	s_nop 0
	s_nop 0
	s_nop 0
	s_nop 0
	s_nop 0
	s_nop 0
	s_nop 0
	s_nop 0
	s_nop 0
	s_nop 0
	s_nop 0
	s_nop 0
	s_nop 0
	s_nop 0
	s_nop 0
	s_nop 0
	s_nop 0
	s_nop 0
	s_nop 0
	s_nop 0
	s_nop 0
	s_nop 0
	s_nop 0
	s_nop 0
	s_nop 0
	s_nop 0
	s_nop 0
	s_nop 0
	s_nop 0
	s_nop 0
	s_nop 0
	s_nop 0
	s_nop 0
	s_nop 0
	s_nop 0
	s_nop 0
	s_nop 0
	s_nop 0
	s_nop 0
	s_nop 0
	s_nop 0
	s_nop 0
	s_nop 0
	s_nop 0
	s_nop 0
	s_nop 0
	s_nop 0
	s_nop 0
	s_nop 0
	s_nop 0
	s_nop 0
	s_nop 0
	s_nop 0
	s_nop 0
	s_nop 0
	s_nop 0
	s_nop 0
	s_nop 0
	s_nop 0
	s_nop 0
	s_nop 0
	s_nop 0
	s_nop 0
	s_nop 0
	s_nop 0
	s_nop 0
	s_nop 0
	s_nop 0
	s_nop 0
	s_nop 0
	s_nop 0
	s_nop 0
	s_nop 0
	s_nop 0
	s_nop 0
	s_nop 0
	s_nop 0
	s_nop 0
	s_nop 0
	s_nop 0
	s_nop 0
	s_nop 0
	s_nop 0
	s_nop 0
	s_nop 0
	s_nop 0
	s_nop 0
	s_nop 0
	s_nop 0
	s_nop 0
	s_nop 0
	s_nop 0
	s_nop 0
	s_nop 0
	s_nop 0
	s_nop 0
	s_nop 0
	s_nop 0
	s_nop 0
	s_nop 0
	s_nop 0
	s_nop 0
	s_nop 0
	s_nop 0
	s_nop 0
	s_nop 0
	s_nop 0
	s_nop 0
	s_nop 0
	s_nop 0
	s_nop 0
	s_nop 0
	s_nop 0
	s_nop 0
	s_nop 0
	s_nop 0
	s_nop 0
	s_nop 0
	s_nop 0
	s_nop 0
	s_nop 0
	s_nop 0
	s_nop 0
	s_nop 0
	s_nop 0
	s_nop 0
	s_nop 0
	s_nop 0
	s_nop 0
	s_nop 0
	s_nop 0
	s_nop 0
	s_nop 0
	s_nop 0
	s_nop 0
	s_nop 0
	s_nop 0
	s_nop 0
	s_nop 0
	s_nop 0
	s_nop 0
	s_nop 0
	s_nop 0
	s_nop 0
	s_nop 0
	s_nop 0
	s_nop 0
	s_nop 0
	s_nop 0
	s_nop 0
	s_nop 0
	s_nop 0
	s_nop 0
	s_nop 0
	s_nop 0
	s_nop 0
	s_nop 0
	s_nop 0
	s_nop 0
	s_nop 0
	s_nop 0
	s_nop 0
	s_nop 0
	s_nop 0
	s_nop 0
	s_nop 0
	s_nop 0
	s_nop 0
	s_nop 0
	s_nop 0
	s_nop 0
	s_nop 0
	s_nop 0
	s_nop 0
	s_nop 0
	s_nop 0
	s_nop 0
	s_nop 0
	s_nop 0
	s_nop 0
	s_nop 0
	s_nop 0
	s_nop 0
	s_nop 0
	s_nop 0
	s_nop 0
	s_nop 0
	s_nop 0
	s_nop 0
	s_nop 0
	s_nop 0
	s_nop 0
	s_nop 0
	s_nop 0
	s_nop 0
	s_nop 0
	s_nop 0
	s_nop 0
	s_nop 0
	s_nop 0
	s_nop 0
	s_nop 0
	s_nop 0
	s_nop 0
	s_nop 0
	s_nop 0
	s_nop 0
	s_nop 0
	s_nop 0
	s_nop 0
	s_nop 0
	s_nop 0
	s_nop 0
	s_nop 0
	s_nop 0
	s_nop 0
	s_nop 0
	s_nop 0
	s_nop 0
	s_nop 0
	s_nop 0
	s_nop 0
	s_nop 0
	s_nop 0
	s_nop 0
	s_nop 0
	s_nop 0
	s_nop 0
	s_nop 0
	s_nop 0
	s_nop 0
	s_nop 0
	s_nop 0
	s_nop 0
	s_nop 0
	s_nop 0
	s_nop 0
	s_nop 0
	s_nop 0
	s_nop 0
	s_nop 0
	s_nop 0
	s_nop 0
	s_nop 0
	s_nop 0
	s_nop 0
	s_nop 0
	s_nop 0
	s_nop 0
	s_nop 0
	s_nop 0
	s_nop 0
	s_nop 0
	s_nop 0
	s_nop 0
	s_nop 0
	s_nop 0
	s_nop 0
	s_nop 0
	s_nop 0
	s_nop 0
	s_nop 0
	s_nop 0
	s_nop 0
	s_nop 0
	s_nop 0
	s_nop 0
	s_nop 0
	s_nop 0
	s_nop 0
	s_nop 0
	s_nop 0
	s_nop 0
	s_nop 0
	s_nop 0
	s_nop 0
	s_nop 0
	s_nop 0
	s_nop 0
	s_nop 0
	s_nop 0
	s_nop 0
	s_nop 0
	s_nop 0
	s_nop 0
	s_nop 0
	s_nop 0
	s_nop 0
	s_nop 0
	s_nop 0
	s_nop 0
	s_nop 0
	s_nop 0
	s_nop 0
	s_nop 0
	s_nop 0
	s_nop 0
	s_nop 0
	s_nop 0
	s_nop 0
	s_nop 0
	s_nop 0
	s_nop 0
	s_nop 0
	s_nop 0
	s_nop 0
	s_nop 0
	s_nop 0
	s_nop 0
	s_nop 0
	s_nop 0
	s_nop 0
	s_nop 0
	s_nop 0
	s_nop 0
	s_nop 0
	s_nop 0
	s_nop 0
	s_nop 0
	s_nop 0
	s_nop 0
	s_nop 0
	s_nop 0
	s_nop 0
	s_nop 0
	s_nop 0
	s_nop 0
	s_nop 0
	s_nop 0
	s_nop 0
	s_nop 0
	s_nop 0
	s_nop 0
	s_nop 0
	s_nop 0
	s_nop 0
	s_nop 0
	s_nop 0
	s_nop 0
	s_nop 0
	s_nop 0
	s_nop 0
	s_nop 0
	s_nop 0
	s_nop 0
	s_nop 0
	s_nop 0
	s_nop 0
	s_nop 0
	s_nop 0
	s_nop 0
	s_nop 0
	s_nop 0
	s_nop 0
	s_nop 0
	s_nop 0
	s_nop 0
	s_nop 0
	s_nop 0
	s_nop 0
	s_nop 0
	s_nop 0
	s_nop 0
	s_nop 0
	s_nop 0
	s_nop 0
	s_nop 0
	s_nop 0
	s_nop 0
	s_nop 0
	s_nop 0
	s_nop 0
	s_nop 0
	s_nop 0
	s_nop 0
	s_nop 0
	s_nop 0
	s_nop 0
	s_nop 0
	s_nop 0
	s_nop 0
	s_nop 0
	s_nop 0
	s_nop 0
	s_nop 0
	s_nop 0
	s_nop 0
	s_nop 0
	s_nop 0
	s_nop 0
	s_nop 0
	s_nop 0
	s_nop 0
	s_nop 0
	s_nop 0
	s_nop 0
	s_nop 0
	s_nop 0
	s_nop 0
	s_nop 0
	s_nop 0
	s_nop 0
	s_nop 0
	s_nop 0
	s_nop 0
	s_nop 0
	s_nop 0
	s_nop 0
	s_nop 0
	s_nop 0
	s_nop 0
	s_nop 0
	s_nop 0
	s_nop 0
	s_nop 0
	s_nop 0
	s_nop 0
	s_nop 0
	s_nop 0
	s_nop 0
	s_nop 0
	s_nop 0
	s_nop 0
	s_nop 0
	s_nop 0
	s_nop 0
	s_nop 0
	s_nop 0
	s_nop 0
	s_nop 0
	s_nop 0
	s_nop 0
	s_nop 0
	s_nop 0
	s_nop 0
	s_nop 0
	s_nop 0
	s_nop 0
	s_nop 0
	s_nop 0
	s_nop 0
	s_nop 0
	s_nop 0
	s_nop 0
	s_nop 0
	s_nop 0
	s_nop 0
	s_nop 0
	s_nop 0
	s_nop 0
	s_nop 0
	s_nop 0
	s_nop 0
	s_nop 0
	s_nop 0
	s_nop 0
	s_nop 0
	s_nop 0
	s_nop 0
	s_nop 0
	s_nop 0
	s_nop 0
	s_nop 0
	s_nop 0
	s_nop 0
	s_nop 0
	s_nop 0
	s_nop 0
	s_nop 0
	s_nop 0
	s_nop 0
	s_nop 0
	s_nop 0
	s_nop 0
	s_nop 0
	s_nop 0
	s_nop 0
	s_nop 0
	s_nop 0
	s_nop 0
	s_nop 0
	s_nop 0
	s_nop 0
	s_nop 0
	s_nop 0
	s_nop 0
	s_nop 0
	s_nop 0
	s_nop 0
	s_nop 0
	s_nop 0
	s_nop 0
	s_nop 0
	s_nop 0
	s_nop 0
	s_nop 0
	s_nop 0
	s_nop 0
	s_nop 0
	s_nop 0
	s_nop 0
	s_nop 0
	s_nop 0
	s_nop 0
	s_nop 0
	s_nop 0
	s_nop 0
	s_nop 0
	s_nop 0
	s_nop 0
	s_nop 0
	s_nop 0
	s_nop 0
	s_nop 0
	s_nop 0
	s_nop 0
	s_nop 0
	s_nop 0
	s_nop 0
	s_nop 0
	s_nop 0
	s_nop 0
	s_nop 0
	s_nop 0
	s_nop 0
	s_nop 0
	s_nop 0
	s_nop 0
	s_nop 0
	s_nop 0
	s_nop 0
	s_nop 0
	s_nop 0
	s_nop 0
	s_nop 0
	s_nop 0
	s_nop 0
